# P3 epilogue rewritten by hand as well (row factors read up front, packed scale + sum of squares, permlane butterflies, SGPR store addressing)
# baseline (speedup 1.0000x reference)
; __device__ __forceinline__ unsigned cvt_pk_bf16(float lo, float hi) { unsigned r; asm volatile("v_cvt_pk_bf16_f32 %0, %1, %2" : "=v"(r) : "v"(lo), "v"(hi)); return r; }
; __device__ __forceinline__ float silu_f(float x) { return x * __builtin_amdgcn_rcpf(1.0f + __builtin_amdgcn_exp2f(-x * LOG2E)); }
;     __device__ __forceinline__ void operator()(const f32x4 (&acc)[2][2][4][2], const pg8::Unit& u, int wr, int wc, int fr, int fq, const LAS float* tab) const {
;     ...
;                 const float f2 = (kind == 4) ? tab[512 + ai * 128 + wr * 64 + m * 16 + fr] : 1.0f;
; #pragma unroll
;                 for (int bj = 0; bj < 2; ++bj) {
;                     f32x4 v0 = acc[ai][bj][m][0], v1 = acc[ai][bj][m][1];
;                     if (kind == 1) {
; #pragma unroll
;                         for (int e = 0; e < 4; ++e) { v0[e] = silu_f(v0[e]); v1[e] = silu_f(v1[e]); }
;                     } else if (kind == 2) { v0 = v0 * QSCALE; v1 = v1 * QSCALE; }
;                     else if (kind == 3) {
; #pragma unroll
;                         for (int e = 0; e < 4; ++e) { s1 += v0[e] + v1[e]; s2 += v0[e] * v0[e] + v1[e] * v1[e]; }
;                     } else if (kind == 4) {
;                         v0 = v0 * f2; v1 = v1 * f2;
; #pragma unroll
;                         for (int e = 0; e < 4; ++e) s2 += v0[e] * v0[e] + v1[e] * v1[e];
;                     }
;                     u32x4 w; w.x = cvt_pk_bf16(v0[0], v0[1]); w.y = cvt_pk_bf16(v0[2], v0[3]); w.z = cvt_pk_bf16(v1[0], v1[1]); w.w = cvt_pk_bf16(v1[2], v1[3]);
;                     *(u32x4*)(rowp + bj * bjstep) = w;
;                 }
;                 if (kind == 3) {
;                     s1 += __shfl_xor(s1, 16); s1 += __shfl_xor(s1, 32); s2 += __shfl_xor(s2, 16); s2 += __shfl_xor(s2, 32);
;                     if (fq == 0) { float* p = aux + (size_t)row * 32 + ((pn - 12) * 4 + wc) * 2; p[0] = s1; p[1] = s2; }
;                 } else if (kind == 4) {
;                     s2 += __shfl_xor(s2, 16); s2 += __shfl_xor(s2, 32);
;                     if (fq == 0) aux[(size_t)row * 32 + pn * 4 + wc] = s2;
.LBB0_761:
	ds_read_b32 v226, v158 offset:2048
	ds_read_b32 v228, v158 offset:2112
	ds_read_b32 v230, v158 offset:2176
	ds_read_b32 v232, v158 offset:2240
	ds_read_b32 v234, v158 offset:2560
	ds_read_b32 v236, v158 offset:2624
	ds_read_b32 v238, v158 offset:2688
	ds_read_b32 v240, v158 offset:2752
	v_and_b32_e32 v224, 15, v157
	v_bfe_u32 v225, v157, 4, 2
	v_lshlrev_b32_e32 v242, 7, v224
	v_lshlrev_b32_e32 v224, 12, v224
	v_lshl_or_b32 v224, v225, 4, v224
	s_lshl_b32 s90, s70, 8
	s_lshr_b32 s91, s33, 2
	s_lshl_b32 s91, s91, 6
	s_add_i32 s90, s90, s91
	s_and_b32 s91, s33, 3
	s_lshl_b32 s92, s90, 12
	s_lshl_b32 s93, s14, 9
	s_add_u32 s92, s92, s93
	s_lshl_b32 s93, s91, 6
	s_add_u32 s92, s92, s93
	s_add_u32 s86, s30, s92
	s_addc_u32 s87, s31, 0
	s_lshl_b32 s92, s90, 7
	s_lshl_b32 s93, s14, 2
	s_add_i32 s93, s93, s91
	s_lshl_b32 s93, s93, 2
	s_add_u32 s92, s92, s93
	s_add_u32 s88, s12, s92
	s_addc_u32 s89, s13, 0
	s_waitcnt lgkmcnt(0)
	v_pk_mul_f32 v[130:131], v[130:131], v[226:227] op_sel_hi:[1,0]
	v_pk_mul_f32 v[132:133], v[132:133], v[226:227] op_sel_hi:[1,0]
	v_pk_mul_f32 v[126:127], v[126:127], v[226:227] op_sel_hi:[1,0]
	v_pk_mul_f32 v[128:129], v[128:129], v[226:227] op_sel_hi:[1,0]
	v_pk_mul_f32 v[122:123], v[122:123], v[226:227] op_sel_hi:[1,0]
	v_pk_mul_f32 v[124:125], v[124:125], v[226:227] op_sel_hi:[1,0]
	v_pk_mul_f32 v[118:119], v[118:119], v[226:227] op_sel_hi:[1,0]
	v_pk_mul_f32 v[120:121], v[120:121], v[226:227] op_sel_hi:[1,0]
	v_pk_mul_f32 v[244:245], v[130:131], v[130:131]
	v_pk_fma_f32 v[244:245], v[132:133], v[132:133], v[244:245]
	v_pk_fma_f32 v[244:245], v[126:127], v[126:127], v[244:245]
	v_pk_fma_f32 v[244:245], v[128:129], v[128:129], v[244:245]
	v_pk_fma_f32 v[244:245], v[122:123], v[122:123], v[244:245]
	v_pk_fma_f32 v[244:245], v[124:125], v[124:125], v[244:245]
	v_pk_fma_f32 v[244:245], v[118:119], v[118:119], v[244:245]
	v_pk_fma_f32 v[244:245], v[120:121], v[120:121], v[244:245]
	v_add_f32_e32 v244, v244, v245
	v_mov_b32_e32 v245, v244
	s_nop 1
	v_permlane16_swap_b32_e32 v245, v244
	v_add_f32_e32 v244, v244, v245
	v_mov_b32_e32 v245, v244
	s_nop 1
	v_permlane32_swap_b32_e32 v245, v244
	v_add_f32_e32 v243, v244, v245
	v_cvt_pk_bf16_f32 v246, v130, v131
	v_cvt_pk_bf16_f32 v247, v132, v133
	v_cvt_pk_bf16_f32 v248, v126, v127
	v_cvt_pk_bf16_f32 v249, v128, v129
	global_store_dwordx4 v224, v[246:249], s[86:87]
	v_cvt_pk_bf16_f32 v250, v122, v123
	v_cvt_pk_bf16_f32 v251, v124, v125
	v_cvt_pk_bf16_f32 v252, v118, v119
	v_cvt_pk_bf16_f32 v253, v120, v121
	global_store_dwordx4 v224, v[250:253], s[86:87] offset:256
	s_and_saveexec_b64 vcc, s[8:9]
	global_store_dword v242, v243, s[88:89]
	s_or_b64 exec, exec, vcc
	s_add_u32 s86, s86, 0x10000
	s_addc_u32 s87, s87, 0
	s_add_u32 s88, s88, 0x800
	s_addc_u32 s89, s89, 0
	v_pk_mul_f32 v[114:115], v[114:115], v[228:229] op_sel_hi:[1,0]
	v_pk_mul_f32 v[116:117], v[116:117], v[228:229] op_sel_hi:[1,0]
	v_pk_mul_f32 v[110:111], v[110:111], v[228:229] op_sel_hi:[1,0]
	v_pk_mul_f32 v[112:113], v[112:113], v[228:229] op_sel_hi:[1,0]
	v_pk_mul_f32 v[106:107], v[106:107], v[228:229] op_sel_hi:[1,0]
	v_pk_mul_f32 v[108:109], v[108:109], v[228:229] op_sel_hi:[1,0]
	v_pk_mul_f32 v[102:103], v[102:103], v[228:229] op_sel_hi:[1,0]
	v_pk_mul_f32 v[104:105], v[104:105], v[228:229] op_sel_hi:[1,0]
	v_pk_mul_f32 v[244:245], v[114:115], v[114:115]
	v_pk_fma_f32 v[244:245], v[116:117], v[116:117], v[244:245]
	v_pk_fma_f32 v[244:245], v[110:111], v[110:111], v[244:245]
	v_pk_fma_f32 v[244:245], v[112:113], v[112:113], v[244:245]
	v_pk_fma_f32 v[244:245], v[106:107], v[106:107], v[244:245]
	v_pk_fma_f32 v[244:245], v[108:109], v[108:109], v[244:245]
	v_pk_fma_f32 v[244:245], v[102:103], v[102:103], v[244:245]
	v_pk_fma_f32 v[244:245], v[104:105], v[104:105], v[244:245]
	v_add_f32_e32 v244, v244, v245
	v_mov_b32_e32 v245, v244
	s_nop 1
	v_permlane16_swap_b32_e32 v245, v244
	v_add_f32_e32 v244, v244, v245
	v_mov_b32_e32 v245, v244
	s_nop 1
	v_permlane32_swap_b32_e32 v245, v244
	v_add_f32_e32 v243, v244, v245
	v_cvt_pk_bf16_f32 v246, v114, v115
	v_cvt_pk_bf16_f32 v247, v116, v117
	v_cvt_pk_bf16_f32 v248, v110, v111
	v_cvt_pk_bf16_f32 v249, v112, v113
	global_store_dwordx4 v224, v[246:249], s[86:87]
	v_cvt_pk_bf16_f32 v250, v106, v107
	v_cvt_pk_bf16_f32 v251, v108, v109
	v_cvt_pk_bf16_f32 v252, v102, v103
	v_cvt_pk_bf16_f32 v253, v104, v105
	global_store_dwordx4 v224, v[250:253], s[86:87] offset:256
	s_and_saveexec_b64 vcc, s[8:9]
	global_store_dword v242, v243, s[88:89]
	s_or_b64 exec, exec, vcc
	s_add_u32 s86, s86, 0x10000
	s_addc_u32 s87, s87, 0
	s_add_u32 s88, s88, 0x800
	s_addc_u32 s89, s89, 0
	v_pk_mul_f32 v[98:99], v[98:99], v[230:231] op_sel_hi:[1,0]
	v_pk_mul_f32 v[100:101], v[100:101], v[230:231] op_sel_hi:[1,0]
	v_pk_mul_f32 v[94:95], v[94:95], v[230:231] op_sel_hi:[1,0]
	v_pk_mul_f32 v[96:97], v[96:97], v[230:231] op_sel_hi:[1,0]
	v_pk_mul_f32 v[90:91], v[90:91], v[230:231] op_sel_hi:[1,0]
	v_pk_mul_f32 v[92:93], v[92:93], v[230:231] op_sel_hi:[1,0]
	v_pk_mul_f32 v[86:87], v[86:87], v[230:231] op_sel_hi:[1,0]
	v_pk_mul_f32 v[88:89], v[88:89], v[230:231] op_sel_hi:[1,0]
	v_pk_mul_f32 v[244:245], v[98:99], v[98:99]
	v_pk_fma_f32 v[244:245], v[100:101], v[100:101], v[244:245]
	v_pk_fma_f32 v[244:245], v[94:95], v[94:95], v[244:245]
	v_pk_fma_f32 v[244:245], v[96:97], v[96:97], v[244:245]
	v_pk_fma_f32 v[244:245], v[90:91], v[90:91], v[244:245]
	v_pk_fma_f32 v[244:245], v[92:93], v[92:93], v[244:245]
	v_pk_fma_f32 v[244:245], v[86:87], v[86:87], v[244:245]
	v_pk_fma_f32 v[244:245], v[88:89], v[88:89], v[244:245]
	v_add_f32_e32 v244, v244, v245
	v_mov_b32_e32 v245, v244
	s_nop 1
; __device__ __forceinline__ unsigned cvt_pk_bf16(float lo, float hi) { unsigned r; asm volatile("v_cvt_pk_bf16_f32 %0, %1, %2" : "=v"(r) : "v"(lo), "v"(hi)); return r; }
; __device__ __forceinline__ float silu_f(float x) { return x * __builtin_amdgcn_rcpf(1.0f + __builtin_amdgcn_exp2f(-x * LOG2E)); }
;     __device__ __forceinline__ void operator()(const f32x4 (&acc)[2][2][4][2], const pg8::Unit& u, int wr, int wc, int fr, int fq, const LAS float* tab) const {
;     ...
;                 const float f2 = (kind == 4) ? tab[512 + ai * 128 + wr * 64 + m * 16 + fr] : 1.0f;
; #pragma unroll
;                 for (int bj = 0; bj < 2; ++bj) {
;                     f32x4 v0 = acc[ai][bj][m][0], v1 = acc[ai][bj][m][1];
;                     if (kind == 1) {
; #pragma unroll
;                         for (int e = 0; e < 4; ++e) { v0[e] = silu_f(v0[e]); v1[e] = silu_f(v1[e]); }
;                     } else if (kind == 2) { v0 = v0 * QSCALE; v1 = v1 * QSCALE; }
;                     else if (kind == 3) {
; #pragma unroll
;                         for (int e = 0; e < 4; ++e) { s1 += v0[e] + v1[e]; s2 += v0[e] * v0[e] + v1[e] * v1[e]; }
;                     } else if (kind == 4) {
;                         v0 = v0 * f2; v1 = v1 * f2;
; #pragma unroll
;                         for (int e = 0; e < 4; ++e) s2 += v0[e] * v0[e] + v1[e] * v1[e];
;                     }
;                     u32x4 w; w.x = cvt_pk_bf16(v0[0], v0[1]); w.y = cvt_pk_bf16(v0[2], v0[3]); w.z = cvt_pk_bf16(v1[0], v1[1]); w.w = cvt_pk_bf16(v1[2], v1[3]);
;                     *(u32x4*)(rowp + bj * bjstep) = w;
;                 }
;                 if (kind == 3) {
;                     s1 += __shfl_xor(s1, 16); s1 += __shfl_xor(s1, 32); s2 += __shfl_xor(s2, 16); s2 += __shfl_xor(s2, 32);
;                     if (fq == 0) { float* p = aux + (size_t)row * 32 + ((pn - 12) * 4 + wc) * 2; p[0] = s1; p[1] = s2; }
;                 } else if (kind == 4) {
;                     s2 += __shfl_xor(s2, 16); s2 += __shfl_xor(s2, 32);
;                     if (fq == 0) aux[(size_t)row * 32 + pn * 4 + wc] = s2;
	v_permlane16_swap_b32_e32 v245, v244
	v_add_f32_e32 v244, v244, v245
	v_mov_b32_e32 v245, v244
	s_nop 1
	v_permlane32_swap_b32_e32 v245, v244
	v_add_f32_e32 v243, v244, v245
	v_cvt_pk_bf16_f32 v246, v98, v99
	v_cvt_pk_bf16_f32 v247, v100, v101
	v_cvt_pk_bf16_f32 v248, v94, v95
	v_cvt_pk_bf16_f32 v249, v96, v97
	global_store_dwordx4 v224, v[246:249], s[86:87]
	v_cvt_pk_bf16_f32 v250, v90, v91
	v_cvt_pk_bf16_f32 v251, v92, v93
	v_cvt_pk_bf16_f32 v252, v86, v87
	v_cvt_pk_bf16_f32 v253, v88, v89
	global_store_dwordx4 v224, v[250:253], s[86:87] offset:256
	s_and_saveexec_b64 vcc, s[8:9]
	global_store_dword v242, v243, s[88:89]
	s_or_b64 exec, exec, vcc
	s_add_u32 s86, s86, 0x10000
	s_addc_u32 s87, s87, 0
	s_add_u32 s88, s88, 0x800
	s_addc_u32 s89, s89, 0
	v_pk_mul_f32 v[82:83], v[82:83], v[232:233] op_sel_hi:[1,0]
	v_pk_mul_f32 v[84:85], v[84:85], v[232:233] op_sel_hi:[1,0]
	v_pk_mul_f32 v[78:79], v[78:79], v[232:233] op_sel_hi:[1,0]
	v_pk_mul_f32 v[80:81], v[80:81], v[232:233] op_sel_hi:[1,0]
	v_pk_mul_f32 v[74:75], v[74:75], v[232:233] op_sel_hi:[1,0]
	v_pk_mul_f32 v[76:77], v[76:77], v[232:233] op_sel_hi:[1,0]
	v_pk_mul_f32 v[70:71], v[70:71], v[232:233] op_sel_hi:[1,0]
	v_pk_mul_f32 v[72:73], v[72:73], v[232:233] op_sel_hi:[1,0]
	v_pk_mul_f32 v[244:245], v[82:83], v[82:83]
	v_pk_fma_f32 v[244:245], v[84:85], v[84:85], v[244:245]
	v_pk_fma_f32 v[244:245], v[78:79], v[78:79], v[244:245]
	v_pk_fma_f32 v[244:245], v[80:81], v[80:81], v[244:245]
	v_pk_fma_f32 v[244:245], v[74:75], v[74:75], v[244:245]
	v_pk_fma_f32 v[244:245], v[76:77], v[76:77], v[244:245]
	v_pk_fma_f32 v[244:245], v[70:71], v[70:71], v[244:245]
	v_pk_fma_f32 v[244:245], v[72:73], v[72:73], v[244:245]
	v_add_f32_e32 v244, v244, v245
	v_mov_b32_e32 v245, v244
	s_nop 1
	v_permlane16_swap_b32_e32 v245, v244
	v_add_f32_e32 v244, v244, v245
	v_mov_b32_e32 v245, v244
	s_nop 1
	v_permlane32_swap_b32_e32 v245, v244
	v_add_f32_e32 v243, v244, v245
	v_cvt_pk_bf16_f32 v246, v82, v83
	v_cvt_pk_bf16_f32 v247, v84, v85
	v_cvt_pk_bf16_f32 v248, v78, v79
	v_cvt_pk_bf16_f32 v249, v80, v81
	global_store_dwordx4 v224, v[246:249], s[86:87]
	v_cvt_pk_bf16_f32 v250, v74, v75
	v_cvt_pk_bf16_f32 v251, v76, v77
	v_cvt_pk_bf16_f32 v252, v70, v71
	v_cvt_pk_bf16_f32 v253, v72, v73
	global_store_dwordx4 v224, v[250:253], s[86:87] offset:256
	s_and_saveexec_b64 vcc, s[8:9]
	global_store_dword v242, v243, s[88:89]
	s_or_b64 exec, exec, vcc
	s_add_u32 s86, s86, 0x50000
	s_addc_u32 s87, s87, 0
	s_add_u32 s88, s88, 0x2800
	s_addc_u32 s89, s89, 0
	v_pk_mul_f32 v[66:67], v[66:67], v[234:235] op_sel_hi:[1,0]
	v_pk_mul_f32 v[68:69], v[68:69], v[234:235] op_sel_hi:[1,0]
	v_pk_mul_f32 v[62:63], v[62:63], v[234:235] op_sel_hi:[1,0]
	v_pk_mul_f32 v[64:65], v[64:65], v[234:235] op_sel_hi:[1,0]
	v_pk_mul_f32 v[58:59], v[58:59], v[234:235] op_sel_hi:[1,0]
	v_pk_mul_f32 v[60:61], v[60:61], v[234:235] op_sel_hi:[1,0]
	v_pk_mul_f32 v[54:55], v[54:55], v[234:235] op_sel_hi:[1,0]
	v_pk_mul_f32 v[56:57], v[56:57], v[234:235] op_sel_hi:[1,0]
	v_pk_mul_f32 v[244:245], v[66:67], v[66:67]
	v_pk_fma_f32 v[244:245], v[68:69], v[68:69], v[244:245]
	v_pk_fma_f32 v[244:245], v[62:63], v[62:63], v[244:245]
	v_pk_fma_f32 v[244:245], v[64:65], v[64:65], v[244:245]
	v_pk_fma_f32 v[244:245], v[58:59], v[58:59], v[244:245]
	v_pk_fma_f32 v[244:245], v[60:61], v[60:61], v[244:245]
	v_pk_fma_f32 v[244:245], v[54:55], v[54:55], v[244:245]
	v_pk_fma_f32 v[244:245], v[56:57], v[56:57], v[244:245]
	v_add_f32_e32 v244, v244, v245
	v_mov_b32_e32 v245, v244
	s_nop 1
	v_permlane16_swap_b32_e32 v245, v244
	v_add_f32_e32 v244, v244, v245
	v_mov_b32_e32 v245, v244
	s_nop 1
	v_permlane32_swap_b32_e32 v245, v244
	v_add_f32_e32 v243, v244, v245
	v_cvt_pk_bf16_f32 v246, v66, v67
	v_cvt_pk_bf16_f32 v247, v68, v69
	v_cvt_pk_bf16_f32 v248, v62, v63
	v_cvt_pk_bf16_f32 v249, v64, v65
	global_store_dwordx4 v224, v[246:249], s[86:87]
	v_cvt_pk_bf16_f32 v250, v58, v59
	v_cvt_pk_bf16_f32 v251, v60, v61
	v_cvt_pk_bf16_f32 v252, v54, v55
	v_cvt_pk_bf16_f32 v253, v56, v57
	global_store_dwordx4 v224, v[250:253], s[86:87] offset:256
	s_and_saveexec_b64 vcc, s[8:9]
	global_store_dword v242, v243, s[88:89]
	s_or_b64 exec, exec, vcc
	s_add_u32 s86, s86, 0x10000
	s_addc_u32 s87, s87, 0
	s_add_u32 s88, s88, 0x800
	s_addc_u32 s89, s89, 0
	v_pk_mul_f32 v[50:51], v[50:51], v[236:237] op_sel_hi:[1,0]
	v_pk_mul_f32 v[52:53], v[52:53], v[236:237] op_sel_hi:[1,0]
	v_pk_mul_f32 v[46:47], v[46:47], v[236:237] op_sel_hi:[1,0]
	v_pk_mul_f32 v[48:49], v[48:49], v[236:237] op_sel_hi:[1,0]
	v_pk_mul_f32 v[42:43], v[42:43], v[236:237] op_sel_hi:[1,0]
	v_pk_mul_f32 v[44:45], v[44:45], v[236:237] op_sel_hi:[1,0]
	v_pk_mul_f32 v[38:39], v[38:39], v[236:237] op_sel_hi:[1,0]
	v_pk_mul_f32 v[40:41], v[40:41], v[236:237] op_sel_hi:[1,0]
; __device__ __forceinline__ unsigned cvt_pk_bf16(float lo, float hi) { unsigned r; asm volatile("v_cvt_pk_bf16_f32 %0, %1, %2" : "=v"(r) : "v"(lo), "v"(hi)); return r; }
; __device__ __forceinline__ float silu_f(float x) { return x * __builtin_amdgcn_rcpf(1.0f + __builtin_amdgcn_exp2f(-x * LOG2E)); }
;     __device__ __forceinline__ void operator()(const f32x4 (&acc)[2][2][4][2], const pg8::Unit& u, int wr, int wc, int fr, int fq, const LAS float* tab) const {
;     ...
;                 const float f2 = (kind == 4) ? tab[512 + ai * 128 + wr * 64 + m * 16 + fr] : 1.0f;
; #pragma unroll
;                 for (int bj = 0; bj < 2; ++bj) {
;                     f32x4 v0 = acc[ai][bj][m][0], v1 = acc[ai][bj][m][1];
;                     if (kind == 1) {
; #pragma unroll
;                         for (int e = 0; e < 4; ++e) { v0[e] = silu_f(v0[e]); v1[e] = silu_f(v1[e]); }
;                     } else if (kind == 2) { v0 = v0 * QSCALE; v1 = v1 * QSCALE; }
;                     else if (kind == 3) {
; #pragma unroll
;                         for (int e = 0; e < 4; ++e) { s1 += v0[e] + v1[e]; s2 += v0[e] * v0[e] + v1[e] * v1[e]; }
;                     } else if (kind == 4) {
;                         v0 = v0 * f2; v1 = v1 * f2;
; #pragma unroll
;                         for (int e = 0; e < 4; ++e) s2 += v0[e] * v0[e] + v1[e] * v1[e];
;                     }
;                     u32x4 w; w.x = cvt_pk_bf16(v0[0], v0[1]); w.y = cvt_pk_bf16(v0[2], v0[3]); w.z = cvt_pk_bf16(v1[0], v1[1]); w.w = cvt_pk_bf16(v1[2], v1[3]);
;                     *(u32x4*)(rowp + bj * bjstep) = w;
;                 }
;                 if (kind == 3) {
;                     s1 += __shfl_xor(s1, 16); s1 += __shfl_xor(s1, 32); s2 += __shfl_xor(s2, 16); s2 += __shfl_xor(s2, 32);
;                     if (fq == 0) { float* p = aux + (size_t)row * 32 + ((pn - 12) * 4 + wc) * 2; p[0] = s1; p[1] = s2; }
;                 } else if (kind == 4) {
;                     s2 += __shfl_xor(s2, 16); s2 += __shfl_xor(s2, 32);
;                     if (fq == 0) aux[(size_t)row * 32 + pn * 4 + wc] = s2;
	v_pk_mul_f32 v[244:245], v[50:51], v[50:51]
	v_pk_fma_f32 v[244:245], v[52:53], v[52:53], v[244:245]
	v_pk_fma_f32 v[244:245], v[46:47], v[46:47], v[244:245]
	v_pk_fma_f32 v[244:245], v[48:49], v[48:49], v[244:245]
	v_pk_fma_f32 v[244:245], v[42:43], v[42:43], v[244:245]
	v_pk_fma_f32 v[244:245], v[44:45], v[44:45], v[244:245]
	v_pk_fma_f32 v[244:245], v[38:39], v[38:39], v[244:245]
	v_pk_fma_f32 v[244:245], v[40:41], v[40:41], v[244:245]
	v_add_f32_e32 v244, v244, v245
	v_mov_b32_e32 v245, v244
	s_nop 1
	v_permlane16_swap_b32_e32 v245, v244
	v_add_f32_e32 v244, v244, v245
	v_mov_b32_e32 v245, v244
	s_nop 1
	v_permlane32_swap_b32_e32 v245, v244
	v_add_f32_e32 v243, v244, v245
	v_cvt_pk_bf16_f32 v246, v50, v51
	v_cvt_pk_bf16_f32 v247, v52, v53
	v_cvt_pk_bf16_f32 v248, v46, v47
	v_cvt_pk_bf16_f32 v249, v48, v49
	global_store_dwordx4 v224, v[246:249], s[86:87]
	v_cvt_pk_bf16_f32 v250, v42, v43
	v_cvt_pk_bf16_f32 v251, v44, v45
	v_cvt_pk_bf16_f32 v252, v38, v39
	v_cvt_pk_bf16_f32 v253, v40, v41
	global_store_dwordx4 v224, v[250:253], s[86:87] offset:256
	s_and_saveexec_b64 vcc, s[8:9]
	global_store_dword v242, v243, s[88:89]
	s_or_b64 exec, exec, vcc
	s_add_u32 s86, s86, 0x10000
	s_addc_u32 s87, s87, 0
	s_add_u32 s88, s88, 0x800
	s_addc_u32 s89, s89, 0
	v_pk_mul_f32 v[34:35], v[34:35], v[238:239] op_sel_hi:[1,0]
	v_pk_mul_f32 v[36:37], v[36:37], v[238:239] op_sel_hi:[1,0]
	v_pk_mul_f32 v[30:31], v[30:31], v[238:239] op_sel_hi:[1,0]
	v_pk_mul_f32 v[32:33], v[32:33], v[238:239] op_sel_hi:[1,0]
	v_pk_mul_f32 v[26:27], v[26:27], v[238:239] op_sel_hi:[1,0]
	v_pk_mul_f32 v[28:29], v[28:29], v[238:239] op_sel_hi:[1,0]
	v_pk_mul_f32 v[22:23], v[22:23], v[238:239] op_sel_hi:[1,0]
	v_pk_mul_f32 v[24:25], v[24:25], v[238:239] op_sel_hi:[1,0]
	v_pk_mul_f32 v[244:245], v[34:35], v[34:35]
	v_pk_fma_f32 v[244:245], v[36:37], v[36:37], v[244:245]
	v_pk_fma_f32 v[244:245], v[30:31], v[30:31], v[244:245]
	v_pk_fma_f32 v[244:245], v[32:33], v[32:33], v[244:245]
	v_pk_fma_f32 v[244:245], v[26:27], v[26:27], v[244:245]
	v_pk_fma_f32 v[244:245], v[28:29], v[28:29], v[244:245]
	v_pk_fma_f32 v[244:245], v[22:23], v[22:23], v[244:245]
	v_pk_fma_f32 v[244:245], v[24:25], v[24:25], v[244:245]
	v_add_f32_e32 v244, v244, v245
	v_mov_b32_e32 v245, v244
	s_nop 1
	v_permlane16_swap_b32_e32 v245, v244
	v_add_f32_e32 v244, v244, v245
	v_mov_b32_e32 v245, v244
	s_nop 1
	v_permlane32_swap_b32_e32 v245, v244
	v_add_f32_e32 v243, v244, v245
	v_cvt_pk_bf16_f32 v246, v34, v35
	v_cvt_pk_bf16_f32 v247, v36, v37
	v_cvt_pk_bf16_f32 v248, v30, v31
	v_cvt_pk_bf16_f32 v249, v32, v33
	global_store_dwordx4 v224, v[246:249], s[86:87]
	v_cvt_pk_bf16_f32 v250, v26, v27
	v_cvt_pk_bf16_f32 v251, v28, v29
	v_cvt_pk_bf16_f32 v252, v22, v23
	v_cvt_pk_bf16_f32 v253, v24, v25
	global_store_dwordx4 v224, v[250:253], s[86:87] offset:256
	s_and_saveexec_b64 vcc, s[8:9]
	global_store_dword v242, v243, s[88:89]
	s_or_b64 exec, exec, vcc
	s_add_u32 s86, s86, 0x10000
	s_addc_u32 s87, s87, 0
	s_add_u32 s88, s88, 0x800
	s_addc_u32 s89, s89, 0
	v_pk_mul_f32 v[18:19], v[18:19], v[240:241] op_sel_hi:[1,0]
	v_pk_mul_f32 v[20:21], v[20:21], v[240:241] op_sel_hi:[1,0]
	v_pk_mul_f32 v[14:15], v[14:15], v[240:241] op_sel_hi:[1,0]
	v_pk_mul_f32 v[16:17], v[16:17], v[240:241] op_sel_hi:[1,0]
	v_pk_mul_f32 v[10:11], v[10:11], v[240:241] op_sel_hi:[1,0]
	v_pk_mul_f32 v[12:13], v[12:13], v[240:241] op_sel_hi:[1,0]
	v_pk_mul_f32 v[6:7], v[6:7], v[240:241] op_sel_hi:[1,0]
	v_pk_mul_f32 v[8:9], v[8:9], v[240:241] op_sel_hi:[1,0]
	v_pk_mul_f32 v[244:245], v[18:19], v[18:19]
	v_pk_fma_f32 v[244:245], v[20:21], v[20:21], v[244:245]
	v_pk_fma_f32 v[244:245], v[14:15], v[14:15], v[244:245]
	v_pk_fma_f32 v[244:245], v[16:17], v[16:17], v[244:245]
	v_pk_fma_f32 v[244:245], v[10:11], v[10:11], v[244:245]
	v_pk_fma_f32 v[244:245], v[12:13], v[12:13], v[244:245]
	v_pk_fma_f32 v[244:245], v[6:7], v[6:7], v[244:245]
	v_pk_fma_f32 v[244:245], v[8:9], v[8:9], v[244:245]
	v_add_f32_e32 v244, v244, v245
	v_mov_b32_e32 v245, v244
	s_nop 1
	v_permlane16_swap_b32_e32 v245, v244
	v_add_f32_e32 v244, v244, v245
	v_mov_b32_e32 v245, v244
	s_nop 1
	v_permlane32_swap_b32_e32 v245, v244
	v_add_f32_e32 v243, v244, v245
	v_cvt_pk_bf16_f32 v246, v18, v19
	v_cvt_pk_bf16_f32 v247, v20, v21
	v_cvt_pk_bf16_f32 v248, v14, v15
	v_cvt_pk_bf16_f32 v249, v16, v17
	global_store_dwordx4 v224, v[246:249], s[86:87]
	v_cvt_pk_bf16_f32 v250, v10, v11
	v_cvt_pk_bf16_f32 v251, v12, v13
	v_cvt_pk_bf16_f32 v252, v6, v7
	v_cvt_pk_bf16_f32 v253, v8, v9
	global_store_dwordx4 v224, v[250:253], s[86:87] offset:256
	s_and_saveexec_b64 vcc, s[8:9]
	global_store_dword v242, v243, s[88:89]
	s_or_b64 exec, exec, vcc
	s_add_u32 s86, s86, 0x10000
	s_addc_u32 s87, s87, 0
	s_add_u32 s88, s88, 0x800
	s_addc_u32 s89, s89, 0
	s_branch .LBB0_777
